# layer-0 row norm in phase 1 replaced by the deep-prefetch hand-written norm loop
# speedup vs baseline: 1.0067x; 1.0067x over previous
.LBB0_94:
	s_cmp_gt_i32 s44, 1
	s_cselect_b64 s[2:3], -1, 0
	s_cmp_lt_i32 s45, 2
	s_cselect_b64 s[4:5], -1, 0
	s_or_b64 s[2:3], s[2:3], s[4:5]
	s_and_b64 vcc, exec, s[2:3]
	s_cbranch_vccnz .LBB0_295
	s_lshl_b32 s96, s22, 3
	s_lshr_b32 s97, s70, 6
	s_add_u32 s96, s96, s97
	s_lshl_b32 s97, s96, 4
	s_cmpk_ge_u32 s97, 0x8000
	s_cbranch_scc1 .Lnp1_done
	s_load_dwordx2 s[88:89], s[0:1], 0x0
	s_load_dwordx2 s[90:91], s[0:1], 0x18
	s_load_dwordx2 s[92:93], s[0:1], 0x140
	s_load_dwordx2 s[94:95], s[0:1], 0x158
	v_mbcnt_hi_u32_b32 v0, -1, v210
	v_lshlrev_b32_e32 v1, 4, v0
	s_waitcnt lgkmcnt(0)
	s_add_u32 s90, s90, 0
	s_addc_u32 s91, s91, 0
	global_load_dwordx4 v[112:115], v1, s[90:91]
	global_load_dwordx4 v[116:119], v1, s[90:91] offset:1024
	global_load_dwordx4 v[120:123], v1, s[90:91] offset:2048
	global_load_dwordx4 v[124:127], v1, s[90:91] offset:3072
	s_lshr_b32 s98, s97, 12
	s_add_u32 s98, s98, 0
	s_mul_i32 s98, s98, 0x3000
	s_add_u32 s92, s92, s98
	s_addc_u32 s93, s93, 0
	global_load_dwordx4 v[144:147], v1, s[92:93]
	global_load_dwordx4 v[148:151], v1, s[92:93] offset:1024
	global_load_dwordx4 v[152:155], v1, s[92:93] offset:2048
	global_load_dwordx4 v[156:159], v1, s[92:93] offset:3072
	s_add_u32 s92, s92, 0x1000
	s_addc_u32 s93, s93, 0
	global_load_dwordx4 v[128:131], v1, s[92:93]
	global_load_dwordx4 v[132:135], v1, s[92:93] offset:1024
	global_load_dwordx4 v[136:139], v1, s[92:93] offset:2048
	global_load_dwordx4 v[140:143], v1, s[92:93] offset:3072
	s_load_dwordx2 s[90:91], s[0:1], 0x210
	s_load_dwordx2 s[92:93], s[0:1], 0x218
	s_waitcnt vmcnt(0) lgkmcnt(0)
	v_pk_add_f32 v[128:129], v[128:129], 1.0 op_sel_hi:[1,0]
	v_pk_add_f32 v[130:131], v[130:131], 1.0 op_sel_hi:[1,0]
	v_pk_add_f32 v[132:133], v[132:133], 1.0 op_sel_hi:[1,0]
	v_pk_add_f32 v[134:135], v[134:135], 1.0 op_sel_hi:[1,0]
	v_pk_add_f32 v[136:137], v[136:137], 1.0 op_sel_hi:[1,0]
	v_pk_add_f32 v[138:139], v[138:139], 1.0 op_sel_hi:[1,0]
	v_pk_add_f32 v[140:141], v[140:141], 1.0 op_sel_hi:[1,0]
	v_pk_add_f32 v[142:143], v[142:143], 1.0 op_sel_hi:[1,0]
	s_add_u32 s98, s97, 0
	s_lshl_b32 s98, s98, 12
	v_add_u32_e32 v3, s98, v1
	global_load_dwordx4 v[16:19], v3, s[88:89]
	global_load_dwordx4 v[20:23], v3, s[88:89] offset:1024
	global_load_dwordx4 v[24:27], v3, s[88:89] offset:2048
	global_load_dwordx4 v[28:31], v3, s[88:89] offset:3072
	s_add_u32 s98, s97, 1
	s_lshl_b32 s98, s98, 12
	v_add_u32_e32 v3, s98, v1
	global_load_dwordx4 v[32:35], v3, s[88:89]
	global_load_dwordx4 v[36:39], v3, s[88:89] offset:1024
	global_load_dwordx4 v[40:43], v3, s[88:89] offset:2048
	global_load_dwordx4 v[44:47], v3, s[88:89] offset:3072
	s_add_u32 s98, s97, 2
	s_lshl_b32 s98, s98, 12
	v_add_u32_e32 v3, s98, v1
	global_load_dwordx4 v[48:51], v3, s[88:89]
	global_load_dwordx4 v[52:55], v3, s[88:89] offset:1024
	global_load_dwordx4 v[56:59], v3, s[88:89] offset:2048
	global_load_dwordx4 v[60:63], v3, s[88:89] offset:3072
	s_add_u32 s98, s97, 3
	s_lshl_b32 s98, s98, 12
	v_add_u32_e32 v3, s98, v1
	global_load_dwordx4 v[64:67], v3, s[88:89]
	global_load_dwordx4 v[68:71], v3, s[88:89] offset:1024
	global_load_dwordx4 v[72:75], v3, s[88:89] offset:2048
	global_load_dwordx4 v[76:79], v3, s[88:89] offset:3072
	s_add_u32 s98, s97, 4
	s_lshl_b32 s98, s98, 12
	v_add_u32_e32 v3, s98, v1
	global_load_dwordx4 v[80:83], v3, s[88:89]
	global_load_dwordx4 v[84:87], v3, s[88:89] offset:1024
	global_load_dwordx4 v[88:91], v3, s[88:89] offset:2048
	global_load_dwordx4 v[92:95], v3, s[88:89] offset:3072
	s_add_u32 s98, s97, 5
	s_lshl_b32 s98, s98, 12
	v_add_u32_e32 v3, s98, v1
	global_load_dwordx4 v[96:99], v3, s[88:89]
	global_load_dwordx4 v[100:103], v3, s[88:89] offset:1024
	global_load_dwordx4 v[104:107], v3, s[88:89] offset:2048
	global_load_dwordx4 v[108:111], v3, s[88:89] offset:3072
	s_waitcnt vmcnt(20)
	v_mul_f32_e32 v4, v16, v16
	v_fma_f32 v4, v17, v17, v4
	v_fma_f32 v4, v18, v18, v4
	v_fma_f32 v4, v19, v19, v4
	v_fma_f32 v4, v20, v20, v4
	v_fma_f32 v4, v21, v21, v4
	v_fma_f32 v4, v22, v22, v4
	v_fma_f32 v4, v23, v23, v4
	v_fma_f32 v4, v24, v24, v4
	v_fma_f32 v4, v25, v25, v4
	v_fma_f32 v4, v26, v26, v4
	v_fma_f32 v4, v27, v27, v4
	v_fma_f32 v4, v28, v28, v4
	v_fma_f32 v4, v29, v29, v4
	v_fma_f32 v4, v30, v30, v4
	v_fma_f32 v4, v31, v31, v4
	s_nop 1
	v_add_f32_dpp v5, v4, v4 quad_perm:[1,0,3,2] row_mask:0xf bank_mask:0xf
	s_nop 1
	v_add_f32_dpp v4, v5, v5 quad_perm:[2,3,0,1] row_mask:0xf bank_mask:0xf
	s_nop 1
	v_add_f32_dpp v5, v4, v4 row_half_mirror row_mask:0xf bank_mask:0xf
	s_nop 1
	v_add_f32_dpp v4, v5, v5 row_mirror row_mask:0xf bank_mask:0xf
	s_nop 1
	v_readlane_b32 s98, v4, 0
	v_readlane_b32 s99, v4, 16
	s_nop 3
	v_mov_b32_e32 v5, s98
	v_add_f32_e32 v5, s99, v5
	v_readlane_b32 s98, v4, 32
	v_readlane_b32 s99, v4, 48
	s_nop 3
	v_add_f32_e32 v5, s98, v5
	v_add_f32_e32 v5, s99, v5
	v_mul_f32_e32 v5, 0x3a800000, v5
	v_add_f32_e32 v5, 0x358637bd, v5
	v_rsq_f32_e32 v6, v5
	s_nop 0
	s_add_u32 s98, s97, 0
	v_pk_mul_f32 v[16:17], v[16:17], v[6:7] op_sel_hi:[1,0]
	v_pk_mul_f32 v[18:19], v[18:19], v[6:7] op_sel_hi:[1,0]
	v_pk_mul_f32 v[20:21], v[20:21], v[6:7] op_sel_hi:[1,0]
	v_pk_mul_f32 v[22:23], v[22:23], v[6:7] op_sel_hi:[1,0]
	v_pk_mul_f32 v[24:25], v[24:25], v[6:7] op_sel_hi:[1,0]
	v_pk_mul_f32 v[26:27], v[26:27], v[6:7] op_sel_hi:[1,0]
	v_pk_mul_f32 v[28:29], v[28:29], v[6:7] op_sel_hi:[1,0]
	v_pk_mul_f32 v[30:31], v[30:31], v[6:7] op_sel_hi:[1,0]
	v_pk_mul_f32 v[16:17], v[16:17], v[112:113]
	v_pk_mul_f32 v[18:19], v[18:19], v[114:115]
	v_pk_mul_f32 v[20:21], v[20:21], v[116:117]
	v_pk_mul_f32 v[22:23], v[22:23], v[118:119]
	v_pk_mul_f32 v[24:25], v[24:25], v[120:121]
	v_pk_mul_f32 v[26:27], v[26:27], v[122:123]
	v_pk_mul_f32 v[28:29], v[28:29], v[124:125]
	v_pk_mul_f32 v[30:31], v[30:31], v[126:127]
	v_pk_fma_f32 v[16:17], v[16:17], v[128:129], v[144:145]
	v_pk_fma_f32 v[18:19], v[18:19], v[130:131], v[146:147]
	v_pk_fma_f32 v[20:21], v[20:21], v[132:133], v[148:149]
	v_pk_fma_f32 v[22:23], v[22:23], v[134:135], v[150:151]
	v_pk_fma_f32 v[24:25], v[24:25], v[136:137], v[152:153]
	v_pk_fma_f32 v[26:27], v[26:27], v[138:139], v[154:155]
	v_pk_fma_f32 v[28:29], v[28:29], v[140:141], v[156:157]
	v_pk_fma_f32 v[30:31], v[30:31], v[142:143], v[158:159]
	v_cvt_pk_bf16_f32 v16, v16, v17
	v_cvt_pk_bf16_f32 v17, v18, v19
	v_cvt_pk_bf16_f32 v18, v20, v21
	v_cvt_pk_bf16_f32 v19, v22, v23
	v_cvt_pk_bf16_f32 v20, v24, v25
	v_cvt_pk_bf16_f32 v21, v26, v27
	v_cvt_pk_bf16_f32 v22, v28, v29
	v_cvt_pk_bf16_f32 v23, v30, v31
	s_lshl_b32 s99, s98, 11
	v_lshl_add_u32 v8, v0, 3, s99
	global_store_dwordx2 v8, v[16:17], s[94:95]
	global_store_dwordx2 v8, v[18:19], s[94:95] offset:512
	global_store_dwordx2 v8, v[20:21], s[94:95] offset:1024
	global_store_dwordx2 v8, v[22:23], s[94:95] offset:1536
	s_lshl_b32 s99, s98, 2
	v_mov_b32_e32 v9, s99
	v_mov_b32_e32 v10, 0
	v_cmp_eq_u32_e32 vcc, 0, v0
	s_and_saveexec_b64 s[98:99], vcc
	global_store_dword v9, v10, s[90:91]
	global_store_dword v9, v10, s[92:93]
	s_or_b64 exec, exec, s[98:99]
	s_add_u32 s98, s97, 6
	s_lshl_b32 s98, s98, 12
	v_add_u32_e32 v3, s98, v1
	global_load_dwordx4 v[16:19], v3, s[88:89]
	global_load_dwordx4 v[20:23], v3, s[88:89] offset:1024
	global_load_dwordx4 v[24:27], v3, s[88:89] offset:2048
	global_load_dwordx4 v[28:31], v3, s[88:89] offset:3072
	s_waitcnt vmcnt(26)
	v_mul_f32_e32 v4, v32, v32
	v_fma_f32 v4, v33, v33, v4
	v_fma_f32 v4, v34, v34, v4
	v_fma_f32 v4, v35, v35, v4
	v_fma_f32 v4, v36, v36, v4
	v_fma_f32 v4, v37, v37, v4
	v_fma_f32 v4, v38, v38, v4
	v_fma_f32 v4, v39, v39, v4
	v_fma_f32 v4, v40, v40, v4
	v_fma_f32 v4, v41, v41, v4
	v_fma_f32 v4, v42, v42, v4
	v_fma_f32 v4, v43, v43, v4
	v_fma_f32 v4, v44, v44, v4
	v_fma_f32 v4, v45, v45, v4
	v_fma_f32 v4, v46, v46, v4
	v_fma_f32 v4, v47, v47, v4
	s_nop 1
	v_add_f32_dpp v5, v4, v4 quad_perm:[1,0,3,2] row_mask:0xf bank_mask:0xf
	s_nop 1
	v_add_f32_dpp v4, v5, v5 quad_perm:[2,3,0,1] row_mask:0xf bank_mask:0xf
	s_nop 1
	v_add_f32_dpp v5, v4, v4 row_half_mirror row_mask:0xf bank_mask:0xf
	s_nop 1
	v_add_f32_dpp v4, v5, v5 row_mirror row_mask:0xf bank_mask:0xf
	s_nop 1
	v_readlane_b32 s98, v4, 0
	v_readlane_b32 s99, v4, 16
	s_nop 3
	v_mov_b32_e32 v5, s98
	v_add_f32_e32 v5, s99, v5
	v_readlane_b32 s98, v4, 32
	v_readlane_b32 s99, v4, 48
	s_nop 3
	v_add_f32_e32 v5, s98, v5
	v_add_f32_e32 v5, s99, v5
	v_mul_f32_e32 v5, 0x3a800000, v5
	v_add_f32_e32 v5, 0x358637bd, v5
	v_rsq_f32_e32 v6, v5
	s_nop 0
	s_add_u32 s98, s97, 1
	v_pk_mul_f32 v[32:33], v[32:33], v[6:7] op_sel_hi:[1,0]
	v_pk_mul_f32 v[34:35], v[34:35], v[6:7] op_sel_hi:[1,0]
	v_pk_mul_f32 v[36:37], v[36:37], v[6:7] op_sel_hi:[1,0]
	v_pk_mul_f32 v[38:39], v[38:39], v[6:7] op_sel_hi:[1,0]
	v_pk_mul_f32 v[40:41], v[40:41], v[6:7] op_sel_hi:[1,0]
	v_pk_mul_f32 v[42:43], v[42:43], v[6:7] op_sel_hi:[1,0]
	v_pk_mul_f32 v[44:45], v[44:45], v[6:7] op_sel_hi:[1,0]
	v_pk_mul_f32 v[46:47], v[46:47], v[6:7] op_sel_hi:[1,0]
	v_pk_mul_f32 v[32:33], v[32:33], v[112:113]
	v_pk_mul_f32 v[34:35], v[34:35], v[114:115]
	v_pk_mul_f32 v[36:37], v[36:37], v[116:117]
	v_pk_mul_f32 v[38:39], v[38:39], v[118:119]
	v_pk_mul_f32 v[40:41], v[40:41], v[120:121]
	v_pk_mul_f32 v[42:43], v[42:43], v[122:123]
	v_pk_mul_f32 v[44:45], v[44:45], v[124:125]
	v_pk_mul_f32 v[46:47], v[46:47], v[126:127]
	v_pk_fma_f32 v[32:33], v[32:33], v[128:129], v[144:145]
	v_pk_fma_f32 v[34:35], v[34:35], v[130:131], v[146:147]
	v_pk_fma_f32 v[36:37], v[36:37], v[132:133], v[148:149]
	v_pk_fma_f32 v[38:39], v[38:39], v[134:135], v[150:151]
	v_pk_fma_f32 v[40:41], v[40:41], v[136:137], v[152:153]
	v_pk_fma_f32 v[42:43], v[42:43], v[138:139], v[154:155]
	v_pk_fma_f32 v[44:45], v[44:45], v[140:141], v[156:157]
	v_pk_fma_f32 v[46:47], v[46:47], v[142:143], v[158:159]
	v_cvt_pk_bf16_f32 v32, v32, v33
	v_cvt_pk_bf16_f32 v33, v34, v35
	v_cvt_pk_bf16_f32 v34, v36, v37
	v_cvt_pk_bf16_f32 v35, v38, v39
	v_cvt_pk_bf16_f32 v36, v40, v41
	v_cvt_pk_bf16_f32 v37, v42, v43
	v_cvt_pk_bf16_f32 v38, v44, v45
	v_cvt_pk_bf16_f32 v39, v46, v47
	s_lshl_b32 s99, s98, 11
	v_lshl_add_u32 v8, v0, 3, s99
	global_store_dwordx2 v8, v[32:33], s[94:95]
	global_store_dwordx2 v8, v[34:35], s[94:95] offset:512
	global_store_dwordx2 v8, v[36:37], s[94:95] offset:1024
	global_store_dwordx2 v8, v[38:39], s[94:95] offset:1536
	s_lshl_b32 s99, s98, 2
	v_mov_b32_e32 v9, s99
	v_mov_b32_e32 v10, 0
	v_cmp_eq_u32_e32 vcc, 0, v0
	s_and_saveexec_b64 s[98:99], vcc
	global_store_dword v9, v10, s[90:91]
	global_store_dword v9, v10, s[92:93]
	s_or_b64 exec, exec, s[98:99]
	s_add_u32 s98, s97, 7
	s_lshl_b32 s98, s98, 12
	v_add_u32_e32 v3, s98, v1
	global_load_dwordx4 v[32:35], v3, s[88:89]
	global_load_dwordx4 v[36:39], v3, s[88:89] offset:1024
	global_load_dwordx4 v[40:43], v3, s[88:89] offset:2048
	global_load_dwordx4 v[44:47], v3, s[88:89] offset:3072
	s_waitcnt vmcnt(32)
	v_mul_f32_e32 v4, v48, v48
	v_fma_f32 v4, v49, v49, v4
	v_fma_f32 v4, v50, v50, v4
	v_fma_f32 v4, v51, v51, v4
	v_fma_f32 v4, v52, v52, v4
	v_fma_f32 v4, v53, v53, v4
	v_fma_f32 v4, v54, v54, v4
	v_fma_f32 v4, v55, v55, v4
	v_fma_f32 v4, v56, v56, v4
	v_fma_f32 v4, v57, v57, v4
	v_fma_f32 v4, v58, v58, v4
	v_fma_f32 v4, v59, v59, v4
	v_fma_f32 v4, v60, v60, v4
	v_fma_f32 v4, v61, v61, v4
	v_fma_f32 v4, v62, v62, v4
	v_fma_f32 v4, v63, v63, v4
	s_nop 1
	v_add_f32_dpp v5, v4, v4 quad_perm:[1,0,3,2] row_mask:0xf bank_mask:0xf
	s_nop 1
	v_add_f32_dpp v4, v5, v5 quad_perm:[2,3,0,1] row_mask:0xf bank_mask:0xf
	s_nop 1
	v_add_f32_dpp v5, v4, v4 row_half_mirror row_mask:0xf bank_mask:0xf
	s_nop 1
	v_add_f32_dpp v4, v5, v5 row_mirror row_mask:0xf bank_mask:0xf
	s_nop 1
	v_readlane_b32 s98, v4, 0
	v_readlane_b32 s99, v4, 16
	s_nop 3
	v_mov_b32_e32 v5, s98
	v_add_f32_e32 v5, s99, v5
	v_readlane_b32 s98, v4, 32
	v_readlane_b32 s99, v4, 48
	s_nop 3
	v_add_f32_e32 v5, s98, v5
	v_add_f32_e32 v5, s99, v5
	v_mul_f32_e32 v5, 0x3a800000, v5
	v_add_f32_e32 v5, 0x358637bd, v5
	v_rsq_f32_e32 v6, v5
	s_nop 0
	s_add_u32 s98, s97, 2
	v_pk_mul_f32 v[48:49], v[48:49], v[6:7] op_sel_hi:[1,0]
	v_pk_mul_f32 v[50:51], v[50:51], v[6:7] op_sel_hi:[1,0]
	v_pk_mul_f32 v[52:53], v[52:53], v[6:7] op_sel_hi:[1,0]
	v_pk_mul_f32 v[54:55], v[54:55], v[6:7] op_sel_hi:[1,0]
	v_pk_mul_f32 v[56:57], v[56:57], v[6:7] op_sel_hi:[1,0]
	v_pk_mul_f32 v[58:59], v[58:59], v[6:7] op_sel_hi:[1,0]
	v_pk_mul_f32 v[60:61], v[60:61], v[6:7] op_sel_hi:[1,0]
	v_pk_mul_f32 v[62:63], v[62:63], v[6:7] op_sel_hi:[1,0]
	v_pk_mul_f32 v[48:49], v[48:49], v[112:113]
	v_pk_mul_f32 v[50:51], v[50:51], v[114:115]
	v_pk_mul_f32 v[52:53], v[52:53], v[116:117]
	v_pk_mul_f32 v[54:55], v[54:55], v[118:119]
	v_pk_mul_f32 v[56:57], v[56:57], v[120:121]
	v_pk_mul_f32 v[58:59], v[58:59], v[122:123]
	v_pk_mul_f32 v[60:61], v[60:61], v[124:125]
	v_pk_mul_f32 v[62:63], v[62:63], v[126:127]
	v_pk_fma_f32 v[48:49], v[48:49], v[128:129], v[144:145]
	v_pk_fma_f32 v[50:51], v[50:51], v[130:131], v[146:147]
	v_pk_fma_f32 v[52:53], v[52:53], v[132:133], v[148:149]
	v_pk_fma_f32 v[54:55], v[54:55], v[134:135], v[150:151]
	v_pk_fma_f32 v[56:57], v[56:57], v[136:137], v[152:153]
	v_pk_fma_f32 v[58:59], v[58:59], v[138:139], v[154:155]
	v_pk_fma_f32 v[60:61], v[60:61], v[140:141], v[156:157]
	v_pk_fma_f32 v[62:63], v[62:63], v[142:143], v[158:159]
	v_cvt_pk_bf16_f32 v48, v48, v49
	v_cvt_pk_bf16_f32 v49, v50, v51
	v_cvt_pk_bf16_f32 v50, v52, v53
	v_cvt_pk_bf16_f32 v51, v54, v55
	v_cvt_pk_bf16_f32 v52, v56, v57
	v_cvt_pk_bf16_f32 v53, v58, v59
	v_cvt_pk_bf16_f32 v54, v60, v61
	v_cvt_pk_bf16_f32 v55, v62, v63
	s_lshl_b32 s99, s98, 11
	v_lshl_add_u32 v8, v0, 3, s99
	global_store_dwordx2 v8, v[48:49], s[94:95]
	global_store_dwordx2 v8, v[50:51], s[94:95] offset:512
	global_store_dwordx2 v8, v[52:53], s[94:95] offset:1024
	global_store_dwordx2 v8, v[54:55], s[94:95] offset:1536
	s_lshl_b32 s99, s98, 2
	v_mov_b32_e32 v9, s99
	v_mov_b32_e32 v10, 0
	v_cmp_eq_u32_e32 vcc, 0, v0
	s_and_saveexec_b64 s[98:99], vcc
	global_store_dword v9, v10, s[90:91]
	global_store_dword v9, v10, s[92:93]
	s_or_b64 exec, exec, s[98:99]
	s_add_u32 s98, s97, 8
	s_lshl_b32 s98, s98, 12
	v_add_u32_e32 v3, s98, v1
	global_load_dwordx4 v[48:51], v3, s[88:89]
	global_load_dwordx4 v[52:55], v3, s[88:89] offset:1024
	global_load_dwordx4 v[56:59], v3, s[88:89] offset:2048
	global_load_dwordx4 v[60:63], v3, s[88:89] offset:3072
	s_waitcnt vmcnt(38)
	v_mul_f32_e32 v4, v64, v64
	v_fma_f32 v4, v65, v65, v4
	v_fma_f32 v4, v66, v66, v4
	v_fma_f32 v4, v67, v67, v4
	v_fma_f32 v4, v68, v68, v4
	v_fma_f32 v4, v69, v69, v4
	v_fma_f32 v4, v70, v70, v4
	v_fma_f32 v4, v71, v71, v4
	v_fma_f32 v4, v72, v72, v4
	v_fma_f32 v4, v73, v73, v4
	v_fma_f32 v4, v74, v74, v4
	v_fma_f32 v4, v75, v75, v4
	v_fma_f32 v4, v76, v76, v4
	v_fma_f32 v4, v77, v77, v4
	v_fma_f32 v4, v78, v78, v4
	v_fma_f32 v4, v79, v79, v4
	s_nop 1
	v_add_f32_dpp v5, v4, v4 quad_perm:[1,0,3,2] row_mask:0xf bank_mask:0xf
	s_nop 1
	v_add_f32_dpp v4, v5, v5 quad_perm:[2,3,0,1] row_mask:0xf bank_mask:0xf
	s_nop 1
	v_add_f32_dpp v5, v4, v4 row_half_mirror row_mask:0xf bank_mask:0xf
	s_nop 1
	v_add_f32_dpp v4, v5, v5 row_mirror row_mask:0xf bank_mask:0xf
	s_nop 1
	v_readlane_b32 s98, v4, 0
	v_readlane_b32 s99, v4, 16
	s_nop 3
	v_mov_b32_e32 v5, s98
	v_add_f32_e32 v5, s99, v5
	v_readlane_b32 s98, v4, 32
	v_readlane_b32 s99, v4, 48
	s_nop 3
	v_add_f32_e32 v5, s98, v5
	v_add_f32_e32 v5, s99, v5
	v_mul_f32_e32 v5, 0x3a800000, v5
	v_add_f32_e32 v5, 0x358637bd, v5
	v_rsq_f32_e32 v6, v5
	s_nop 0
	s_add_u32 s98, s97, 3
	v_pk_mul_f32 v[64:65], v[64:65], v[6:7] op_sel_hi:[1,0]
	v_pk_mul_f32 v[66:67], v[66:67], v[6:7] op_sel_hi:[1,0]
	v_pk_mul_f32 v[68:69], v[68:69], v[6:7] op_sel_hi:[1,0]
	v_pk_mul_f32 v[70:71], v[70:71], v[6:7] op_sel_hi:[1,0]
	v_pk_mul_f32 v[72:73], v[72:73], v[6:7] op_sel_hi:[1,0]
	v_pk_mul_f32 v[74:75], v[74:75], v[6:7] op_sel_hi:[1,0]
	v_pk_mul_f32 v[76:77], v[76:77], v[6:7] op_sel_hi:[1,0]
	v_pk_mul_f32 v[78:79], v[78:79], v[6:7] op_sel_hi:[1,0]
	v_pk_mul_f32 v[64:65], v[64:65], v[112:113]
	v_pk_mul_f32 v[66:67], v[66:67], v[114:115]
	v_pk_mul_f32 v[68:69], v[68:69], v[116:117]
	v_pk_mul_f32 v[70:71], v[70:71], v[118:119]
	v_pk_mul_f32 v[72:73], v[72:73], v[120:121]
	v_pk_mul_f32 v[74:75], v[74:75], v[122:123]
	v_pk_mul_f32 v[76:77], v[76:77], v[124:125]
	v_pk_mul_f32 v[78:79], v[78:79], v[126:127]
	v_pk_fma_f32 v[64:65], v[64:65], v[128:129], v[144:145]
	v_pk_fma_f32 v[66:67], v[66:67], v[130:131], v[146:147]
	v_pk_fma_f32 v[68:69], v[68:69], v[132:133], v[148:149]
	v_pk_fma_f32 v[70:71], v[70:71], v[134:135], v[150:151]
	v_pk_fma_f32 v[72:73], v[72:73], v[136:137], v[152:153]
	v_pk_fma_f32 v[74:75], v[74:75], v[138:139], v[154:155]
	v_pk_fma_f32 v[76:77], v[76:77], v[140:141], v[156:157]
	v_pk_fma_f32 v[78:79], v[78:79], v[142:143], v[158:159]
	v_cvt_pk_bf16_f32 v64, v64, v65
	v_cvt_pk_bf16_f32 v65, v66, v67
	v_cvt_pk_bf16_f32 v66, v68, v69
	v_cvt_pk_bf16_f32 v67, v70, v71
	v_cvt_pk_bf16_f32 v68, v72, v73
	v_cvt_pk_bf16_f32 v69, v74, v75
	v_cvt_pk_bf16_f32 v70, v76, v77
	v_cvt_pk_bf16_f32 v71, v78, v79
	s_lshl_b32 s99, s98, 11
	v_lshl_add_u32 v8, v0, 3, s99
	global_store_dwordx2 v8, v[64:65], s[94:95]
	global_store_dwordx2 v8, v[66:67], s[94:95] offset:512
	global_store_dwordx2 v8, v[68:69], s[94:95] offset:1024
	global_store_dwordx2 v8, v[70:71], s[94:95] offset:1536
	s_lshl_b32 s99, s98, 2
	v_mov_b32_e32 v9, s99
	v_mov_b32_e32 v10, 0
	v_cmp_eq_u32_e32 vcc, 0, v0
	s_and_saveexec_b64 s[98:99], vcc
	global_store_dword v9, v10, s[90:91]
	global_store_dword v9, v10, s[92:93]
	s_or_b64 exec, exec, s[98:99]
	s_add_u32 s98, s97, 9
	s_lshl_b32 s98, s98, 12
	v_add_u32_e32 v3, s98, v1
	global_load_dwordx4 v[64:67], v3, s[88:89]
	global_load_dwordx4 v[68:71], v3, s[88:89] offset:1024
	global_load_dwordx4 v[72:75], v3, s[88:89] offset:2048
	global_load_dwordx4 v[76:79], v3, s[88:89] offset:3072
	s_waitcnt vmcnt(44)
	v_mul_f32_e32 v4, v80, v80
	v_fma_f32 v4, v81, v81, v4
	v_fma_f32 v4, v82, v82, v4
	v_fma_f32 v4, v83, v83, v4
	v_fma_f32 v4, v84, v84, v4
	v_fma_f32 v4, v85, v85, v4
	v_fma_f32 v4, v86, v86, v4
	v_fma_f32 v4, v87, v87, v4
	v_fma_f32 v4, v88, v88, v4
	v_fma_f32 v4, v89, v89, v4
	v_fma_f32 v4, v90, v90, v4
	v_fma_f32 v4, v91, v91, v4
	v_fma_f32 v4, v92, v92, v4
	v_fma_f32 v4, v93, v93, v4
	v_fma_f32 v4, v94, v94, v4
	v_fma_f32 v4, v95, v95, v4
	s_nop 1
	v_add_f32_dpp v5, v4, v4 quad_perm:[1,0,3,2] row_mask:0xf bank_mask:0xf
	s_nop 1
	v_add_f32_dpp v4, v5, v5 quad_perm:[2,3,0,1] row_mask:0xf bank_mask:0xf
	s_nop 1
	v_add_f32_dpp v5, v4, v4 row_half_mirror row_mask:0xf bank_mask:0xf
	s_nop 1
	v_add_f32_dpp v4, v5, v5 row_mirror row_mask:0xf bank_mask:0xf
	s_nop 1
	v_readlane_b32 s98, v4, 0
	v_readlane_b32 s99, v4, 16
	s_nop 3
	v_mov_b32_e32 v5, s98
	v_add_f32_e32 v5, s99, v5
	v_readlane_b32 s98, v4, 32
	v_readlane_b32 s99, v4, 48
	s_nop 3
	v_add_f32_e32 v5, s98, v5
	v_add_f32_e32 v5, s99, v5
	v_mul_f32_e32 v5, 0x3a800000, v5
	v_add_f32_e32 v5, 0x358637bd, v5
	v_rsq_f32_e32 v6, v5
	s_nop 0
	s_add_u32 s98, s97, 4
	v_pk_mul_f32 v[80:81], v[80:81], v[6:7] op_sel_hi:[1,0]
	v_pk_mul_f32 v[82:83], v[82:83], v[6:7] op_sel_hi:[1,0]
	v_pk_mul_f32 v[84:85], v[84:85], v[6:7] op_sel_hi:[1,0]
	v_pk_mul_f32 v[86:87], v[86:87], v[6:7] op_sel_hi:[1,0]
	v_pk_mul_f32 v[88:89], v[88:89], v[6:7] op_sel_hi:[1,0]
	v_pk_mul_f32 v[90:91], v[90:91], v[6:7] op_sel_hi:[1,0]
	v_pk_mul_f32 v[92:93], v[92:93], v[6:7] op_sel_hi:[1,0]
	v_pk_mul_f32 v[94:95], v[94:95], v[6:7] op_sel_hi:[1,0]
	v_pk_mul_f32 v[80:81], v[80:81], v[112:113]
	v_pk_mul_f32 v[82:83], v[82:83], v[114:115]
	v_pk_mul_f32 v[84:85], v[84:85], v[116:117]
	v_pk_mul_f32 v[86:87], v[86:87], v[118:119]
	v_pk_mul_f32 v[88:89], v[88:89], v[120:121]
	v_pk_mul_f32 v[90:91], v[90:91], v[122:123]
	v_pk_mul_f32 v[92:93], v[92:93], v[124:125]
	v_pk_mul_f32 v[94:95], v[94:95], v[126:127]
	v_pk_fma_f32 v[80:81], v[80:81], v[128:129], v[144:145]
	v_pk_fma_f32 v[82:83], v[82:83], v[130:131], v[146:147]
	v_pk_fma_f32 v[84:85], v[84:85], v[132:133], v[148:149]
	v_pk_fma_f32 v[86:87], v[86:87], v[134:135], v[150:151]
	v_pk_fma_f32 v[88:89], v[88:89], v[136:137], v[152:153]
	v_pk_fma_f32 v[90:91], v[90:91], v[138:139], v[154:155]
	v_pk_fma_f32 v[92:93], v[92:93], v[140:141], v[156:157]
	v_pk_fma_f32 v[94:95], v[94:95], v[142:143], v[158:159]
	v_cvt_pk_bf16_f32 v80, v80, v81
	v_cvt_pk_bf16_f32 v81, v82, v83
	v_cvt_pk_bf16_f32 v82, v84, v85
	v_cvt_pk_bf16_f32 v83, v86, v87
	v_cvt_pk_bf16_f32 v84, v88, v89
	v_cvt_pk_bf16_f32 v85, v90, v91
	v_cvt_pk_bf16_f32 v86, v92, v93
	v_cvt_pk_bf16_f32 v87, v94, v95
	s_lshl_b32 s99, s98, 11
	v_lshl_add_u32 v8, v0, 3, s99
	global_store_dwordx2 v8, v[80:81], s[94:95]
	global_store_dwordx2 v8, v[82:83], s[94:95] offset:512
	global_store_dwordx2 v8, v[84:85], s[94:95] offset:1024
	global_store_dwordx2 v8, v[86:87], s[94:95] offset:1536
	s_lshl_b32 s99, s98, 2
	v_mov_b32_e32 v9, s99
	v_mov_b32_e32 v10, 0
	v_cmp_eq_u32_e32 vcc, 0, v0
	s_and_saveexec_b64 s[98:99], vcc
	global_store_dword v9, v10, s[90:91]
	global_store_dword v9, v10, s[92:93]
	s_or_b64 exec, exec, s[98:99]
	s_add_u32 s98, s97, 10
	s_lshl_b32 s98, s98, 12
	v_add_u32_e32 v3, s98, v1
	global_load_dwordx4 v[80:83], v3, s[88:89]
	global_load_dwordx4 v[84:87], v3, s[88:89] offset:1024
	global_load_dwordx4 v[88:91], v3, s[88:89] offset:2048
	global_load_dwordx4 v[92:95], v3, s[88:89] offset:3072
	s_waitcnt vmcnt(50)
	v_mul_f32_e32 v4, v96, v96
	v_fma_f32 v4, v97, v97, v4
	v_fma_f32 v4, v98, v98, v4
	v_fma_f32 v4, v99, v99, v4
	v_fma_f32 v4, v100, v100, v4
	v_fma_f32 v4, v101, v101, v4
	v_fma_f32 v4, v102, v102, v4
	v_fma_f32 v4, v103, v103, v4
	v_fma_f32 v4, v104, v104, v4
	v_fma_f32 v4, v105, v105, v4
	v_fma_f32 v4, v106, v106, v4
	v_fma_f32 v4, v107, v107, v4
	v_fma_f32 v4, v108, v108, v4
	v_fma_f32 v4, v109, v109, v4
	v_fma_f32 v4, v110, v110, v4
	v_fma_f32 v4, v111, v111, v4
	s_nop 1
	v_add_f32_dpp v5, v4, v4 quad_perm:[1,0,3,2] row_mask:0xf bank_mask:0xf
	s_nop 1
	v_add_f32_dpp v4, v5, v5 quad_perm:[2,3,0,1] row_mask:0xf bank_mask:0xf
	s_nop 1
	v_add_f32_dpp v5, v4, v4 row_half_mirror row_mask:0xf bank_mask:0xf
	s_nop 1
	v_add_f32_dpp v4, v5, v5 row_mirror row_mask:0xf bank_mask:0xf
	s_nop 1
	v_readlane_b32 s98, v4, 0
	v_readlane_b32 s99, v4, 16
	s_nop 3
	v_mov_b32_e32 v5, s98
	v_add_f32_e32 v5, s99, v5
	v_readlane_b32 s98, v4, 32
	v_readlane_b32 s99, v4, 48
	s_nop 3
	v_add_f32_e32 v5, s98, v5
	v_add_f32_e32 v5, s99, v5
	v_mul_f32_e32 v5, 0x3a800000, v5
	v_add_f32_e32 v5, 0x358637bd, v5
	v_rsq_f32_e32 v6, v5
	s_nop 0
	s_add_u32 s98, s97, 5
	v_pk_mul_f32 v[96:97], v[96:97], v[6:7] op_sel_hi:[1,0]
	v_pk_mul_f32 v[98:99], v[98:99], v[6:7] op_sel_hi:[1,0]
	v_pk_mul_f32 v[100:101], v[100:101], v[6:7] op_sel_hi:[1,0]
	v_pk_mul_f32 v[102:103], v[102:103], v[6:7] op_sel_hi:[1,0]
	v_pk_mul_f32 v[104:105], v[104:105], v[6:7] op_sel_hi:[1,0]
	v_pk_mul_f32 v[106:107], v[106:107], v[6:7] op_sel_hi:[1,0]
	v_pk_mul_f32 v[108:109], v[108:109], v[6:7] op_sel_hi:[1,0]
	v_pk_mul_f32 v[110:111], v[110:111], v[6:7] op_sel_hi:[1,0]
	v_pk_mul_f32 v[96:97], v[96:97], v[112:113]
	v_pk_mul_f32 v[98:99], v[98:99], v[114:115]
	v_pk_mul_f32 v[100:101], v[100:101], v[116:117]
	v_pk_mul_f32 v[102:103], v[102:103], v[118:119]
	v_pk_mul_f32 v[104:105], v[104:105], v[120:121]
	v_pk_mul_f32 v[106:107], v[106:107], v[122:123]
	v_pk_mul_f32 v[108:109], v[108:109], v[124:125]
	v_pk_mul_f32 v[110:111], v[110:111], v[126:127]
	v_pk_fma_f32 v[96:97], v[96:97], v[128:129], v[144:145]
	v_pk_fma_f32 v[98:99], v[98:99], v[130:131], v[146:147]
	v_pk_fma_f32 v[100:101], v[100:101], v[132:133], v[148:149]
	v_pk_fma_f32 v[102:103], v[102:103], v[134:135], v[150:151]
	v_pk_fma_f32 v[104:105], v[104:105], v[136:137], v[152:153]
	v_pk_fma_f32 v[106:107], v[106:107], v[138:139], v[154:155]
	v_pk_fma_f32 v[108:109], v[108:109], v[140:141], v[156:157]
	v_pk_fma_f32 v[110:111], v[110:111], v[142:143], v[158:159]
	v_cvt_pk_bf16_f32 v96, v96, v97
	v_cvt_pk_bf16_f32 v97, v98, v99
	v_cvt_pk_bf16_f32 v98, v100, v101
	v_cvt_pk_bf16_f32 v99, v102, v103
	v_cvt_pk_bf16_f32 v100, v104, v105
	v_cvt_pk_bf16_f32 v101, v106, v107
	v_cvt_pk_bf16_f32 v102, v108, v109
	v_cvt_pk_bf16_f32 v103, v110, v111
	s_lshl_b32 s99, s98, 11
	v_lshl_add_u32 v8, v0, 3, s99
	global_store_dwordx2 v8, v[96:97], s[94:95]
	global_store_dwordx2 v8, v[98:99], s[94:95] offset:512
	global_store_dwordx2 v8, v[100:101], s[94:95] offset:1024
	global_store_dwordx2 v8, v[102:103], s[94:95] offset:1536
	s_lshl_b32 s99, s98, 2
	v_mov_b32_e32 v9, s99
	v_mov_b32_e32 v10, 0
	v_cmp_eq_u32_e32 vcc, 0, v0
	s_and_saveexec_b64 s[98:99], vcc
	global_store_dword v9, v10, s[90:91]
	global_store_dword v9, v10, s[92:93]
	s_or_b64 exec, exec, s[98:99]
	s_add_u32 s98, s97, 11
	s_lshl_b32 s98, s98, 12
	v_add_u32_e32 v3, s98, v1
	global_load_dwordx4 v[96:99], v3, s[88:89]
	global_load_dwordx4 v[100:103], v3, s[88:89] offset:1024
	global_load_dwordx4 v[104:107], v3, s[88:89] offset:2048
	global_load_dwordx4 v[108:111], v3, s[88:89] offset:3072
	s_waitcnt vmcnt(50)
	v_mul_f32_e32 v4, v16, v16
	v_fma_f32 v4, v17, v17, v4
	v_fma_f32 v4, v18, v18, v4
	v_fma_f32 v4, v19, v19, v4
	v_fma_f32 v4, v20, v20, v4
	v_fma_f32 v4, v21, v21, v4
	v_fma_f32 v4, v22, v22, v4
	v_fma_f32 v4, v23, v23, v4
	v_fma_f32 v4, v24, v24, v4
	v_fma_f32 v4, v25, v25, v4
	v_fma_f32 v4, v26, v26, v4
	v_fma_f32 v4, v27, v27, v4
	v_fma_f32 v4, v28, v28, v4
	v_fma_f32 v4, v29, v29, v4
	v_fma_f32 v4, v30, v30, v4
	v_fma_f32 v4, v31, v31, v4
	s_nop 1
	v_add_f32_dpp v5, v4, v4 quad_perm:[1,0,3,2] row_mask:0xf bank_mask:0xf
	s_nop 1
	v_add_f32_dpp v4, v5, v5 quad_perm:[2,3,0,1] row_mask:0xf bank_mask:0xf
	s_nop 1
	v_add_f32_dpp v5, v4, v4 row_half_mirror row_mask:0xf bank_mask:0xf
	s_nop 1
	v_add_f32_dpp v4, v5, v5 row_mirror row_mask:0xf bank_mask:0xf
	s_nop 1
	v_readlane_b32 s98, v4, 0
	v_readlane_b32 s99, v4, 16
	s_nop 3
	v_mov_b32_e32 v5, s98
	v_add_f32_e32 v5, s99, v5
	v_readlane_b32 s98, v4, 32
	v_readlane_b32 s99, v4, 48
	s_nop 3
	v_add_f32_e32 v5, s98, v5
	v_add_f32_e32 v5, s99, v5
	v_mul_f32_e32 v5, 0x3a800000, v5
	v_add_f32_e32 v5, 0x358637bd, v5
	v_rsq_f32_e32 v6, v5
	s_nop 0
	s_add_u32 s98, s97, 6
	v_pk_mul_f32 v[16:17], v[16:17], v[6:7] op_sel_hi:[1,0]
	v_pk_mul_f32 v[18:19], v[18:19], v[6:7] op_sel_hi:[1,0]
	v_pk_mul_f32 v[20:21], v[20:21], v[6:7] op_sel_hi:[1,0]
	v_pk_mul_f32 v[22:23], v[22:23], v[6:7] op_sel_hi:[1,0]
	v_pk_mul_f32 v[24:25], v[24:25], v[6:7] op_sel_hi:[1,0]
	v_pk_mul_f32 v[26:27], v[26:27], v[6:7] op_sel_hi:[1,0]
	v_pk_mul_f32 v[28:29], v[28:29], v[6:7] op_sel_hi:[1,0]
	v_pk_mul_f32 v[30:31], v[30:31], v[6:7] op_sel_hi:[1,0]
	v_pk_mul_f32 v[16:17], v[16:17], v[112:113]
	v_pk_mul_f32 v[18:19], v[18:19], v[114:115]
	v_pk_mul_f32 v[20:21], v[20:21], v[116:117]
	v_pk_mul_f32 v[22:23], v[22:23], v[118:119]
	v_pk_mul_f32 v[24:25], v[24:25], v[120:121]
	v_pk_mul_f32 v[26:27], v[26:27], v[122:123]
	v_pk_mul_f32 v[28:29], v[28:29], v[124:125]
	v_pk_mul_f32 v[30:31], v[30:31], v[126:127]
	v_pk_fma_f32 v[16:17], v[16:17], v[128:129], v[144:145]
	v_pk_fma_f32 v[18:19], v[18:19], v[130:131], v[146:147]
	v_pk_fma_f32 v[20:21], v[20:21], v[132:133], v[148:149]
	v_pk_fma_f32 v[22:23], v[22:23], v[134:135], v[150:151]
	v_pk_fma_f32 v[24:25], v[24:25], v[136:137], v[152:153]
	v_pk_fma_f32 v[26:27], v[26:27], v[138:139], v[154:155]
	v_pk_fma_f32 v[28:29], v[28:29], v[140:141], v[156:157]
	v_pk_fma_f32 v[30:31], v[30:31], v[142:143], v[158:159]
	v_cvt_pk_bf16_f32 v16, v16, v17
	v_cvt_pk_bf16_f32 v17, v18, v19
	v_cvt_pk_bf16_f32 v18, v20, v21
	v_cvt_pk_bf16_f32 v19, v22, v23
	v_cvt_pk_bf16_f32 v20, v24, v25
	v_cvt_pk_bf16_f32 v21, v26, v27
	v_cvt_pk_bf16_f32 v22, v28, v29
	v_cvt_pk_bf16_f32 v23, v30, v31
	s_lshl_b32 s99, s98, 11
	v_lshl_add_u32 v8, v0, 3, s99
	global_store_dwordx2 v8, v[16:17], s[94:95]
	global_store_dwordx2 v8, v[18:19], s[94:95] offset:512
	global_store_dwordx2 v8, v[20:21], s[94:95] offset:1024
	global_store_dwordx2 v8, v[22:23], s[94:95] offset:1536
	s_lshl_b32 s99, s98, 2
	v_mov_b32_e32 v9, s99
	v_mov_b32_e32 v10, 0
	v_cmp_eq_u32_e32 vcc, 0, v0
	s_and_saveexec_b64 s[98:99], vcc
	global_store_dword v9, v10, s[90:91]
	global_store_dword v9, v10, s[92:93]
	s_or_b64 exec, exec, s[98:99]
	s_add_u32 s98, s97, 12
	s_lshl_b32 s98, s98, 12
	v_add_u32_e32 v3, s98, v1
	global_load_dwordx4 v[16:19], v3, s[88:89]
	global_load_dwordx4 v[20:23], v3, s[88:89] offset:1024
	global_load_dwordx4 v[24:27], v3, s[88:89] offset:2048
	global_load_dwordx4 v[28:31], v3, s[88:89] offset:3072
	s_waitcnt vmcnt(50)
	v_mul_f32_e32 v4, v32, v32
	v_fma_f32 v4, v33, v33, v4
	v_fma_f32 v4, v34, v34, v4
	v_fma_f32 v4, v35, v35, v4
	v_fma_f32 v4, v36, v36, v4
	v_fma_f32 v4, v37, v37, v4
	v_fma_f32 v4, v38, v38, v4
	v_fma_f32 v4, v39, v39, v4
	v_fma_f32 v4, v40, v40, v4
	v_fma_f32 v4, v41, v41, v4
	v_fma_f32 v4, v42, v42, v4
	v_fma_f32 v4, v43, v43, v4
	v_fma_f32 v4, v44, v44, v4
	v_fma_f32 v4, v45, v45, v4
	v_fma_f32 v4, v46, v46, v4
	v_fma_f32 v4, v47, v47, v4
	s_nop 1
	v_add_f32_dpp v5, v4, v4 quad_perm:[1,0,3,2] row_mask:0xf bank_mask:0xf
	s_nop 1
	v_add_f32_dpp v4, v5, v5 quad_perm:[2,3,0,1] row_mask:0xf bank_mask:0xf
	s_nop 1
	v_add_f32_dpp v5, v4, v4 row_half_mirror row_mask:0xf bank_mask:0xf
	s_nop 1
	v_add_f32_dpp v4, v5, v5 row_mirror row_mask:0xf bank_mask:0xf
	s_nop 1
	v_readlane_b32 s98, v4, 0
	v_readlane_b32 s99, v4, 16
	s_nop 3
	v_mov_b32_e32 v5, s98
	v_add_f32_e32 v5, s99, v5
	v_readlane_b32 s98, v4, 32
	v_readlane_b32 s99, v4, 48
	s_nop 3
	v_add_f32_e32 v5, s98, v5
	v_add_f32_e32 v5, s99, v5
	v_mul_f32_e32 v5, 0x3a800000, v5
	v_add_f32_e32 v5, 0x358637bd, v5
	v_rsq_f32_e32 v6, v5
	s_nop 0
	s_add_u32 s98, s97, 7
	v_pk_mul_f32 v[32:33], v[32:33], v[6:7] op_sel_hi:[1,0]
	v_pk_mul_f32 v[34:35], v[34:35], v[6:7] op_sel_hi:[1,0]
	v_pk_mul_f32 v[36:37], v[36:37], v[6:7] op_sel_hi:[1,0]
	v_pk_mul_f32 v[38:39], v[38:39], v[6:7] op_sel_hi:[1,0]
	v_pk_mul_f32 v[40:41], v[40:41], v[6:7] op_sel_hi:[1,0]
	v_pk_mul_f32 v[42:43], v[42:43], v[6:7] op_sel_hi:[1,0]
	v_pk_mul_f32 v[44:45], v[44:45], v[6:7] op_sel_hi:[1,0]
	v_pk_mul_f32 v[46:47], v[46:47], v[6:7] op_sel_hi:[1,0]
	v_pk_mul_f32 v[32:33], v[32:33], v[112:113]
	v_pk_mul_f32 v[34:35], v[34:35], v[114:115]
	v_pk_mul_f32 v[36:37], v[36:37], v[116:117]
	v_pk_mul_f32 v[38:39], v[38:39], v[118:119]
	v_pk_mul_f32 v[40:41], v[40:41], v[120:121]
	v_pk_mul_f32 v[42:43], v[42:43], v[122:123]
	v_pk_mul_f32 v[44:45], v[44:45], v[124:125]
	v_pk_mul_f32 v[46:47], v[46:47], v[126:127]
	v_pk_fma_f32 v[32:33], v[32:33], v[128:129], v[144:145]
	v_pk_fma_f32 v[34:35], v[34:35], v[130:131], v[146:147]
	v_pk_fma_f32 v[36:37], v[36:37], v[132:133], v[148:149]
	v_pk_fma_f32 v[38:39], v[38:39], v[134:135], v[150:151]
	v_pk_fma_f32 v[40:41], v[40:41], v[136:137], v[152:153]
	v_pk_fma_f32 v[42:43], v[42:43], v[138:139], v[154:155]
	v_pk_fma_f32 v[44:45], v[44:45], v[140:141], v[156:157]
	v_pk_fma_f32 v[46:47], v[46:47], v[142:143], v[158:159]
	v_cvt_pk_bf16_f32 v32, v32, v33
	v_cvt_pk_bf16_f32 v33, v34, v35
	v_cvt_pk_bf16_f32 v34, v36, v37
	v_cvt_pk_bf16_f32 v35, v38, v39
	v_cvt_pk_bf16_f32 v36, v40, v41
	v_cvt_pk_bf16_f32 v37, v42, v43
	v_cvt_pk_bf16_f32 v38, v44, v45
	v_cvt_pk_bf16_f32 v39, v46, v47
	s_lshl_b32 s99, s98, 11
	v_lshl_add_u32 v8, v0, 3, s99
	global_store_dwordx2 v8, v[32:33], s[94:95]
	global_store_dwordx2 v8, v[34:35], s[94:95] offset:512
	global_store_dwordx2 v8, v[36:37], s[94:95] offset:1024
	global_store_dwordx2 v8, v[38:39], s[94:95] offset:1536
	s_lshl_b32 s99, s98, 2
	v_mov_b32_e32 v9, s99
	v_mov_b32_e32 v10, 0
	v_cmp_eq_u32_e32 vcc, 0, v0
	s_and_saveexec_b64 s[98:99], vcc
	global_store_dword v9, v10, s[90:91]
	global_store_dword v9, v10, s[92:93]
	s_or_b64 exec, exec, s[98:99]
	s_add_u32 s98, s97, 13
	s_lshl_b32 s98, s98, 12
	v_add_u32_e32 v3, s98, v1
	global_load_dwordx4 v[32:35], v3, s[88:89]
	global_load_dwordx4 v[36:39], v3, s[88:89] offset:1024
	global_load_dwordx4 v[40:43], v3, s[88:89] offset:2048
	global_load_dwordx4 v[44:47], v3, s[88:89] offset:3072
	s_waitcnt vmcnt(50)
	v_mul_f32_e32 v4, v48, v48
	v_fma_f32 v4, v49, v49, v4
	v_fma_f32 v4, v50, v50, v4
	v_fma_f32 v4, v51, v51, v4
	v_fma_f32 v4, v52, v52, v4
	v_fma_f32 v4, v53, v53, v4
	v_fma_f32 v4, v54, v54, v4
	v_fma_f32 v4, v55, v55, v4
	v_fma_f32 v4, v56, v56, v4
	v_fma_f32 v4, v57, v57, v4
	v_fma_f32 v4, v58, v58, v4
	v_fma_f32 v4, v59, v59, v4
	v_fma_f32 v4, v60, v60, v4
	v_fma_f32 v4, v61, v61, v4
	v_fma_f32 v4, v62, v62, v4
	v_fma_f32 v4, v63, v63, v4
	s_nop 1
	v_add_f32_dpp v5, v4, v4 quad_perm:[1,0,3,2] row_mask:0xf bank_mask:0xf
	s_nop 1
	v_add_f32_dpp v4, v5, v5 quad_perm:[2,3,0,1] row_mask:0xf bank_mask:0xf
	s_nop 1
	v_add_f32_dpp v5, v4, v4 row_half_mirror row_mask:0xf bank_mask:0xf
	s_nop 1
	v_add_f32_dpp v4, v5, v5 row_mirror row_mask:0xf bank_mask:0xf
	s_nop 1
	v_readlane_b32 s98, v4, 0
	v_readlane_b32 s99, v4, 16
	s_nop 3
	v_mov_b32_e32 v5, s98
	v_add_f32_e32 v5, s99, v5
	v_readlane_b32 s98, v4, 32
	v_readlane_b32 s99, v4, 48
	s_nop 3
	v_add_f32_e32 v5, s98, v5
	v_add_f32_e32 v5, s99, v5
	v_mul_f32_e32 v5, 0x3a800000, v5
	v_add_f32_e32 v5, 0x358637bd, v5
	v_rsq_f32_e32 v6, v5
	s_nop 0
	s_add_u32 s98, s97, 8
	v_pk_mul_f32 v[48:49], v[48:49], v[6:7] op_sel_hi:[1,0]
	v_pk_mul_f32 v[50:51], v[50:51], v[6:7] op_sel_hi:[1,0]
	v_pk_mul_f32 v[52:53], v[52:53], v[6:7] op_sel_hi:[1,0]
	v_pk_mul_f32 v[54:55], v[54:55], v[6:7] op_sel_hi:[1,0]
	v_pk_mul_f32 v[56:57], v[56:57], v[6:7] op_sel_hi:[1,0]
	v_pk_mul_f32 v[58:59], v[58:59], v[6:7] op_sel_hi:[1,0]
	v_pk_mul_f32 v[60:61], v[60:61], v[6:7] op_sel_hi:[1,0]
	v_pk_mul_f32 v[62:63], v[62:63], v[6:7] op_sel_hi:[1,0]
	v_pk_mul_f32 v[48:49], v[48:49], v[112:113]
	v_pk_mul_f32 v[50:51], v[50:51], v[114:115]
	v_pk_mul_f32 v[52:53], v[52:53], v[116:117]
	v_pk_mul_f32 v[54:55], v[54:55], v[118:119]
	v_pk_mul_f32 v[56:57], v[56:57], v[120:121]
	v_pk_mul_f32 v[58:59], v[58:59], v[122:123]
	v_pk_mul_f32 v[60:61], v[60:61], v[124:125]
	v_pk_mul_f32 v[62:63], v[62:63], v[126:127]
	v_pk_fma_f32 v[48:49], v[48:49], v[128:129], v[144:145]
	v_pk_fma_f32 v[50:51], v[50:51], v[130:131], v[146:147]
	v_pk_fma_f32 v[52:53], v[52:53], v[132:133], v[148:149]
	v_pk_fma_f32 v[54:55], v[54:55], v[134:135], v[150:151]
	v_pk_fma_f32 v[56:57], v[56:57], v[136:137], v[152:153]
	v_pk_fma_f32 v[58:59], v[58:59], v[138:139], v[154:155]
	v_pk_fma_f32 v[60:61], v[60:61], v[140:141], v[156:157]
	v_pk_fma_f32 v[62:63], v[62:63], v[142:143], v[158:159]
	v_cvt_pk_bf16_f32 v48, v48, v49
	v_cvt_pk_bf16_f32 v49, v50, v51
	v_cvt_pk_bf16_f32 v50, v52, v53
	v_cvt_pk_bf16_f32 v51, v54, v55
	v_cvt_pk_bf16_f32 v52, v56, v57
	v_cvt_pk_bf16_f32 v53, v58, v59
	v_cvt_pk_bf16_f32 v54, v60, v61
	v_cvt_pk_bf16_f32 v55, v62, v63
	s_lshl_b32 s99, s98, 11
	v_lshl_add_u32 v8, v0, 3, s99
	global_store_dwordx2 v8, v[48:49], s[94:95]
	global_store_dwordx2 v8, v[50:51], s[94:95] offset:512
	global_store_dwordx2 v8, v[52:53], s[94:95] offset:1024
	global_store_dwordx2 v8, v[54:55], s[94:95] offset:1536
	s_lshl_b32 s99, s98, 2
	v_mov_b32_e32 v9, s99
	v_mov_b32_e32 v10, 0
	v_cmp_eq_u32_e32 vcc, 0, v0
	s_and_saveexec_b64 s[98:99], vcc
	global_store_dword v9, v10, s[90:91]
	global_store_dword v9, v10, s[92:93]
	s_or_b64 exec, exec, s[98:99]
	s_add_u32 s98, s97, 14
	s_lshl_b32 s98, s98, 12
	v_add_u32_e32 v3, s98, v1
	global_load_dwordx4 v[48:51], v3, s[88:89]
	global_load_dwordx4 v[52:55], v3, s[88:89] offset:1024
	global_load_dwordx4 v[56:59], v3, s[88:89] offset:2048
	global_load_dwordx4 v[60:63], v3, s[88:89] offset:3072
	s_waitcnt vmcnt(50)
	v_mul_f32_e32 v4, v64, v64
	v_fma_f32 v4, v65, v65, v4
	v_fma_f32 v4, v66, v66, v4
	v_fma_f32 v4, v67, v67, v4
	v_fma_f32 v4, v68, v68, v4
	v_fma_f32 v4, v69, v69, v4
	v_fma_f32 v4, v70, v70, v4
	v_fma_f32 v4, v71, v71, v4
	v_fma_f32 v4, v72, v72, v4
	v_fma_f32 v4, v73, v73, v4
	v_fma_f32 v4, v74, v74, v4
	v_fma_f32 v4, v75, v75, v4
	v_fma_f32 v4, v76, v76, v4
	v_fma_f32 v4, v77, v77, v4
	v_fma_f32 v4, v78, v78, v4
	v_fma_f32 v4, v79, v79, v4
	s_nop 1
	v_add_f32_dpp v5, v4, v4 quad_perm:[1,0,3,2] row_mask:0xf bank_mask:0xf
	s_nop 1
	v_add_f32_dpp v4, v5, v5 quad_perm:[2,3,0,1] row_mask:0xf bank_mask:0xf
	s_nop 1
	v_add_f32_dpp v5, v4, v4 row_half_mirror row_mask:0xf bank_mask:0xf
	s_nop 1
	v_add_f32_dpp v4, v5, v5 row_mirror row_mask:0xf bank_mask:0xf
	s_nop 1
	v_readlane_b32 s98, v4, 0
	v_readlane_b32 s99, v4, 16
	s_nop 3
	v_mov_b32_e32 v5, s98
	v_add_f32_e32 v5, s99, v5
	v_readlane_b32 s98, v4, 32
	v_readlane_b32 s99, v4, 48
	s_nop 3
	v_add_f32_e32 v5, s98, v5
	v_add_f32_e32 v5, s99, v5
	v_mul_f32_e32 v5, 0x3a800000, v5
	v_add_f32_e32 v5, 0x358637bd, v5
	v_rsq_f32_e32 v6, v5
	s_nop 0
	s_add_u32 s98, s97, 9
	v_pk_mul_f32 v[64:65], v[64:65], v[6:7] op_sel_hi:[1,0]
	v_pk_mul_f32 v[66:67], v[66:67], v[6:7] op_sel_hi:[1,0]
	v_pk_mul_f32 v[68:69], v[68:69], v[6:7] op_sel_hi:[1,0]
	v_pk_mul_f32 v[70:71], v[70:71], v[6:7] op_sel_hi:[1,0]
	v_pk_mul_f32 v[72:73], v[72:73], v[6:7] op_sel_hi:[1,0]
	v_pk_mul_f32 v[74:75], v[74:75], v[6:7] op_sel_hi:[1,0]
	v_pk_mul_f32 v[76:77], v[76:77], v[6:7] op_sel_hi:[1,0]
	v_pk_mul_f32 v[78:79], v[78:79], v[6:7] op_sel_hi:[1,0]
	v_pk_mul_f32 v[64:65], v[64:65], v[112:113]
	v_pk_mul_f32 v[66:67], v[66:67], v[114:115]
	v_pk_mul_f32 v[68:69], v[68:69], v[116:117]
	v_pk_mul_f32 v[70:71], v[70:71], v[118:119]
	v_pk_mul_f32 v[72:73], v[72:73], v[120:121]
	v_pk_mul_f32 v[74:75], v[74:75], v[122:123]
	v_pk_mul_f32 v[76:77], v[76:77], v[124:125]
	v_pk_mul_f32 v[78:79], v[78:79], v[126:127]
	v_pk_fma_f32 v[64:65], v[64:65], v[128:129], v[144:145]
	v_pk_fma_f32 v[66:67], v[66:67], v[130:131], v[146:147]
	v_pk_fma_f32 v[68:69], v[68:69], v[132:133], v[148:149]
	v_pk_fma_f32 v[70:71], v[70:71], v[134:135], v[150:151]
	v_pk_fma_f32 v[72:73], v[72:73], v[136:137], v[152:153]
	v_pk_fma_f32 v[74:75], v[74:75], v[138:139], v[154:155]
	v_pk_fma_f32 v[76:77], v[76:77], v[140:141], v[156:157]
	v_pk_fma_f32 v[78:79], v[78:79], v[142:143], v[158:159]
	v_cvt_pk_bf16_f32 v64, v64, v65
	v_cvt_pk_bf16_f32 v65, v66, v67
	v_cvt_pk_bf16_f32 v66, v68, v69
	v_cvt_pk_bf16_f32 v67, v70, v71
	v_cvt_pk_bf16_f32 v68, v72, v73
	v_cvt_pk_bf16_f32 v69, v74, v75
	v_cvt_pk_bf16_f32 v70, v76, v77
	v_cvt_pk_bf16_f32 v71, v78, v79
	s_lshl_b32 s99, s98, 11
	v_lshl_add_u32 v8, v0, 3, s99
	global_store_dwordx2 v8, v[64:65], s[94:95]
	global_store_dwordx2 v8, v[66:67], s[94:95] offset:512
	global_store_dwordx2 v8, v[68:69], s[94:95] offset:1024
	global_store_dwordx2 v8, v[70:71], s[94:95] offset:1536
	s_lshl_b32 s99, s98, 2
	v_mov_b32_e32 v9, s99
	v_mov_b32_e32 v10, 0
	v_cmp_eq_u32_e32 vcc, 0, v0
	s_and_saveexec_b64 s[98:99], vcc
	global_store_dword v9, v10, s[90:91]
	global_store_dword v9, v10, s[92:93]
	s_or_b64 exec, exec, s[98:99]
	s_add_u32 s98, s97, 15
	s_lshl_b32 s98, s98, 12
	v_add_u32_e32 v3, s98, v1
	global_load_dwordx4 v[64:67], v3, s[88:89]
	global_load_dwordx4 v[68:71], v3, s[88:89] offset:1024
	global_load_dwordx4 v[72:75], v3, s[88:89] offset:2048
	global_load_dwordx4 v[76:79], v3, s[88:89] offset:3072
	s_waitcnt vmcnt(50)
	v_mul_f32_e32 v4, v80, v80
	v_fma_f32 v4, v81, v81, v4
	v_fma_f32 v4, v82, v82, v4
	v_fma_f32 v4, v83, v83, v4
	v_fma_f32 v4, v84, v84, v4
	v_fma_f32 v4, v85, v85, v4
	v_fma_f32 v4, v86, v86, v4
	v_fma_f32 v4, v87, v87, v4
	v_fma_f32 v4, v88, v88, v4
	v_fma_f32 v4, v89, v89, v4
	v_fma_f32 v4, v90, v90, v4
	v_fma_f32 v4, v91, v91, v4
	v_fma_f32 v4, v92, v92, v4
	v_fma_f32 v4, v93, v93, v4
	v_fma_f32 v4, v94, v94, v4
	v_fma_f32 v4, v95, v95, v4
	s_nop 1
	v_add_f32_dpp v5, v4, v4 quad_perm:[1,0,3,2] row_mask:0xf bank_mask:0xf
	s_nop 1
	v_add_f32_dpp v4, v5, v5 quad_perm:[2,3,0,1] row_mask:0xf bank_mask:0xf
	s_nop 1
	v_add_f32_dpp v5, v4, v4 row_half_mirror row_mask:0xf bank_mask:0xf
	s_nop 1
	v_add_f32_dpp v4, v5, v5 row_mirror row_mask:0xf bank_mask:0xf
	s_nop 1
	v_readlane_b32 s98, v4, 0
	v_readlane_b32 s99, v4, 16
	s_nop 3
	v_mov_b32_e32 v5, s98
	v_add_f32_e32 v5, s99, v5
	v_readlane_b32 s98, v4, 32
	v_readlane_b32 s99, v4, 48
	s_nop 3
	v_add_f32_e32 v5, s98, v5
	v_add_f32_e32 v5, s99, v5
	v_mul_f32_e32 v5, 0x3a800000, v5
	v_add_f32_e32 v5, 0x358637bd, v5
	v_rsq_f32_e32 v6, v5
	s_nop 0
	s_add_u32 s98, s97, 10
	v_pk_mul_f32 v[80:81], v[80:81], v[6:7] op_sel_hi:[1,0]
	v_pk_mul_f32 v[82:83], v[82:83], v[6:7] op_sel_hi:[1,0]
	v_pk_mul_f32 v[84:85], v[84:85], v[6:7] op_sel_hi:[1,0]
	v_pk_mul_f32 v[86:87], v[86:87], v[6:7] op_sel_hi:[1,0]
	v_pk_mul_f32 v[88:89], v[88:89], v[6:7] op_sel_hi:[1,0]
	v_pk_mul_f32 v[90:91], v[90:91], v[6:7] op_sel_hi:[1,0]
	v_pk_mul_f32 v[92:93], v[92:93], v[6:7] op_sel_hi:[1,0]
	v_pk_mul_f32 v[94:95], v[94:95], v[6:7] op_sel_hi:[1,0]
	v_pk_mul_f32 v[80:81], v[80:81], v[112:113]
	v_pk_mul_f32 v[82:83], v[82:83], v[114:115]
	v_pk_mul_f32 v[84:85], v[84:85], v[116:117]
	v_pk_mul_f32 v[86:87], v[86:87], v[118:119]
	v_pk_mul_f32 v[88:89], v[88:89], v[120:121]
	v_pk_mul_f32 v[90:91], v[90:91], v[122:123]
	v_pk_mul_f32 v[92:93], v[92:93], v[124:125]
	v_pk_mul_f32 v[94:95], v[94:95], v[126:127]
	v_pk_fma_f32 v[80:81], v[80:81], v[128:129], v[144:145]
	v_pk_fma_f32 v[82:83], v[82:83], v[130:131], v[146:147]
	v_pk_fma_f32 v[84:85], v[84:85], v[132:133], v[148:149]
	v_pk_fma_f32 v[86:87], v[86:87], v[134:135], v[150:151]
	v_pk_fma_f32 v[88:89], v[88:89], v[136:137], v[152:153]
	v_pk_fma_f32 v[90:91], v[90:91], v[138:139], v[154:155]
	v_pk_fma_f32 v[92:93], v[92:93], v[140:141], v[156:157]
	v_pk_fma_f32 v[94:95], v[94:95], v[142:143], v[158:159]
	v_cvt_pk_bf16_f32 v80, v80, v81
	v_cvt_pk_bf16_f32 v81, v82, v83
	v_cvt_pk_bf16_f32 v82, v84, v85
	v_cvt_pk_bf16_f32 v83, v86, v87
	v_cvt_pk_bf16_f32 v84, v88, v89
	v_cvt_pk_bf16_f32 v85, v90, v91
	v_cvt_pk_bf16_f32 v86, v92, v93
	v_cvt_pk_bf16_f32 v87, v94, v95
	s_lshl_b32 s99, s98, 11
	v_lshl_add_u32 v8, v0, 3, s99
	global_store_dwordx2 v8, v[80:81], s[94:95]
	global_store_dwordx2 v8, v[82:83], s[94:95] offset:512
	global_store_dwordx2 v8, v[84:85], s[94:95] offset:1024
	global_store_dwordx2 v8, v[86:87], s[94:95] offset:1536
	s_lshl_b32 s99, s98, 2
	v_mov_b32_e32 v9, s99
	v_mov_b32_e32 v10, 0
	v_cmp_eq_u32_e32 vcc, 0, v0
	s_and_saveexec_b64 s[98:99], vcc
	global_store_dword v9, v10, s[90:91]
	global_store_dword v9, v10, s[92:93]
	s_or_b64 exec, exec, s[98:99]
	s_waitcnt vmcnt(46)
	v_mul_f32_e32 v4, v96, v96
	v_fma_f32 v4, v97, v97, v4
	v_fma_f32 v4, v98, v98, v4
	v_fma_f32 v4, v99, v99, v4
	v_fma_f32 v4, v100, v100, v4
	v_fma_f32 v4, v101, v101, v4
	v_fma_f32 v4, v102, v102, v4
	v_fma_f32 v4, v103, v103, v4
	v_fma_f32 v4, v104, v104, v4
	v_fma_f32 v4, v105, v105, v4
	v_fma_f32 v4, v106, v106, v4
	v_fma_f32 v4, v107, v107, v4
	v_fma_f32 v4, v108, v108, v4
	v_fma_f32 v4, v109, v109, v4
	v_fma_f32 v4, v110, v110, v4
	v_fma_f32 v4, v111, v111, v4
	s_nop 1
	v_add_f32_dpp v5, v4, v4 quad_perm:[1,0,3,2] row_mask:0xf bank_mask:0xf
	s_nop 1
	v_add_f32_dpp v4, v5, v5 quad_perm:[2,3,0,1] row_mask:0xf bank_mask:0xf
	s_nop 1
	v_add_f32_dpp v5, v4, v4 row_half_mirror row_mask:0xf bank_mask:0xf
	s_nop 1
	v_add_f32_dpp v4, v5, v5 row_mirror row_mask:0xf bank_mask:0xf
	s_nop 1
	v_readlane_b32 s98, v4, 0
	v_readlane_b32 s99, v4, 16
	s_nop 3
	v_mov_b32_e32 v5, s98
	v_add_f32_e32 v5, s99, v5
	v_readlane_b32 s98, v4, 32
	v_readlane_b32 s99, v4, 48
	s_nop 3
	v_add_f32_e32 v5, s98, v5
	v_add_f32_e32 v5, s99, v5
	v_mul_f32_e32 v5, 0x3a800000, v5
	v_add_f32_e32 v5, 0x358637bd, v5
	v_rsq_f32_e32 v6, v5
	s_nop 0
	s_add_u32 s98, s97, 11
	v_pk_mul_f32 v[96:97], v[96:97], v[6:7] op_sel_hi:[1,0]
	v_pk_mul_f32 v[98:99], v[98:99], v[6:7] op_sel_hi:[1,0]
	v_pk_mul_f32 v[100:101], v[100:101], v[6:7] op_sel_hi:[1,0]
	v_pk_mul_f32 v[102:103], v[102:103], v[6:7] op_sel_hi:[1,0]
	v_pk_mul_f32 v[104:105], v[104:105], v[6:7] op_sel_hi:[1,0]
	v_pk_mul_f32 v[106:107], v[106:107], v[6:7] op_sel_hi:[1,0]
	v_pk_mul_f32 v[108:109], v[108:109], v[6:7] op_sel_hi:[1,0]
	v_pk_mul_f32 v[110:111], v[110:111], v[6:7] op_sel_hi:[1,0]
	v_pk_mul_f32 v[96:97], v[96:97], v[112:113]
	v_pk_mul_f32 v[98:99], v[98:99], v[114:115]
	v_pk_mul_f32 v[100:101], v[100:101], v[116:117]
	v_pk_mul_f32 v[102:103], v[102:103], v[118:119]
	v_pk_mul_f32 v[104:105], v[104:105], v[120:121]
	v_pk_mul_f32 v[106:107], v[106:107], v[122:123]
	v_pk_mul_f32 v[108:109], v[108:109], v[124:125]
	v_pk_mul_f32 v[110:111], v[110:111], v[126:127]
	v_pk_fma_f32 v[96:97], v[96:97], v[128:129], v[144:145]
	v_pk_fma_f32 v[98:99], v[98:99], v[130:131], v[146:147]
	v_pk_fma_f32 v[100:101], v[100:101], v[132:133], v[148:149]
	v_pk_fma_f32 v[102:103], v[102:103], v[134:135], v[150:151]
	v_pk_fma_f32 v[104:105], v[104:105], v[136:137], v[152:153]
	v_pk_fma_f32 v[106:107], v[106:107], v[138:139], v[154:155]
	v_pk_fma_f32 v[108:109], v[108:109], v[140:141], v[156:157]
	v_pk_fma_f32 v[110:111], v[110:111], v[142:143], v[158:159]
	v_cvt_pk_bf16_f32 v96, v96, v97
	v_cvt_pk_bf16_f32 v97, v98, v99
	v_cvt_pk_bf16_f32 v98, v100, v101
	v_cvt_pk_bf16_f32 v99, v102, v103
	v_cvt_pk_bf16_f32 v100, v104, v105
	v_cvt_pk_bf16_f32 v101, v106, v107
	v_cvt_pk_bf16_f32 v102, v108, v109
	v_cvt_pk_bf16_f32 v103, v110, v111
	s_lshl_b32 s99, s98, 11
	v_lshl_add_u32 v8, v0, 3, s99
	global_store_dwordx2 v8, v[96:97], s[94:95]
	global_store_dwordx2 v8, v[98:99], s[94:95] offset:512
	global_store_dwordx2 v8, v[100:101], s[94:95] offset:1024
	global_store_dwordx2 v8, v[102:103], s[94:95] offset:1536
	s_lshl_b32 s99, s98, 2
	v_mov_b32_e32 v9, s99
	v_mov_b32_e32 v10, 0
	v_cmp_eq_u32_e32 vcc, 0, v0
	s_and_saveexec_b64 s[98:99], vcc
	global_store_dword v9, v10, s[90:91]
	global_store_dword v9, v10, s[92:93]
	s_or_b64 exec, exec, s[98:99]
	s_waitcnt vmcnt(42)
	v_mul_f32_e32 v4, v16, v16
	v_fma_f32 v4, v17, v17, v4
	v_fma_f32 v4, v18, v18, v4
	v_fma_f32 v4, v19, v19, v4
	v_fma_f32 v4, v20, v20, v4
	v_fma_f32 v4, v21, v21, v4
	v_fma_f32 v4, v22, v22, v4
	v_fma_f32 v4, v23, v23, v4
	v_fma_f32 v4, v24, v24, v4
	v_fma_f32 v4, v25, v25, v4
	v_fma_f32 v4, v26, v26, v4
	v_fma_f32 v4, v27, v27, v4
	v_fma_f32 v4, v28, v28, v4
	v_fma_f32 v4, v29, v29, v4
	v_fma_f32 v4, v30, v30, v4
	v_fma_f32 v4, v31, v31, v4
	s_nop 1
	v_add_f32_dpp v5, v4, v4 quad_perm:[1,0,3,2] row_mask:0xf bank_mask:0xf
	s_nop 1
	v_add_f32_dpp v4, v5, v5 quad_perm:[2,3,0,1] row_mask:0xf bank_mask:0xf
	s_nop 1
	v_add_f32_dpp v5, v4, v4 row_half_mirror row_mask:0xf bank_mask:0xf
	s_nop 1
	v_add_f32_dpp v4, v5, v5 row_mirror row_mask:0xf bank_mask:0xf
	s_nop 1
	v_readlane_b32 s98, v4, 0
	v_readlane_b32 s99, v4, 16
	s_nop 3
	v_mov_b32_e32 v5, s98
	v_add_f32_e32 v5, s99, v5
	v_readlane_b32 s98, v4, 32
	v_readlane_b32 s99, v4, 48
	s_nop 3
	v_add_f32_e32 v5, s98, v5
	v_add_f32_e32 v5, s99, v5
	v_mul_f32_e32 v5, 0x3a800000, v5
	v_add_f32_e32 v5, 0x358637bd, v5
	v_rsq_f32_e32 v6, v5
	s_nop 0
	s_add_u32 s98, s97, 12
	v_pk_mul_f32 v[16:17], v[16:17], v[6:7] op_sel_hi:[1,0]
	v_pk_mul_f32 v[18:19], v[18:19], v[6:7] op_sel_hi:[1,0]
	v_pk_mul_f32 v[20:21], v[20:21], v[6:7] op_sel_hi:[1,0]
	v_pk_mul_f32 v[22:23], v[22:23], v[6:7] op_sel_hi:[1,0]
	v_pk_mul_f32 v[24:25], v[24:25], v[6:7] op_sel_hi:[1,0]
	v_pk_mul_f32 v[26:27], v[26:27], v[6:7] op_sel_hi:[1,0]
	v_pk_mul_f32 v[28:29], v[28:29], v[6:7] op_sel_hi:[1,0]
	v_pk_mul_f32 v[30:31], v[30:31], v[6:7] op_sel_hi:[1,0]
	v_pk_mul_f32 v[16:17], v[16:17], v[112:113]
	v_pk_mul_f32 v[18:19], v[18:19], v[114:115]
	v_pk_mul_f32 v[20:21], v[20:21], v[116:117]
	v_pk_mul_f32 v[22:23], v[22:23], v[118:119]
	v_pk_mul_f32 v[24:25], v[24:25], v[120:121]
	v_pk_mul_f32 v[26:27], v[26:27], v[122:123]
	v_pk_mul_f32 v[28:29], v[28:29], v[124:125]
	v_pk_mul_f32 v[30:31], v[30:31], v[126:127]
	v_pk_fma_f32 v[16:17], v[16:17], v[128:129], v[144:145]
	v_pk_fma_f32 v[18:19], v[18:19], v[130:131], v[146:147]
	v_pk_fma_f32 v[20:21], v[20:21], v[132:133], v[148:149]
	v_pk_fma_f32 v[22:23], v[22:23], v[134:135], v[150:151]
	v_pk_fma_f32 v[24:25], v[24:25], v[136:137], v[152:153]
	v_pk_fma_f32 v[26:27], v[26:27], v[138:139], v[154:155]
	v_pk_fma_f32 v[28:29], v[28:29], v[140:141], v[156:157]
	v_pk_fma_f32 v[30:31], v[30:31], v[142:143], v[158:159]
	v_cvt_pk_bf16_f32 v16, v16, v17
	v_cvt_pk_bf16_f32 v17, v18, v19
	v_cvt_pk_bf16_f32 v18, v20, v21
	v_cvt_pk_bf16_f32 v19, v22, v23
	v_cvt_pk_bf16_f32 v20, v24, v25
	v_cvt_pk_bf16_f32 v21, v26, v27
	v_cvt_pk_bf16_f32 v22, v28, v29
	v_cvt_pk_bf16_f32 v23, v30, v31
	s_lshl_b32 s99, s98, 11
	v_lshl_add_u32 v8, v0, 3, s99
	global_store_dwordx2 v8, v[16:17], s[94:95]
	global_store_dwordx2 v8, v[18:19], s[94:95] offset:512
	global_store_dwordx2 v8, v[20:21], s[94:95] offset:1024
	global_store_dwordx2 v8, v[22:23], s[94:95] offset:1536
	s_lshl_b32 s99, s98, 2
	v_mov_b32_e32 v9, s99
	v_mov_b32_e32 v10, 0
	v_cmp_eq_u32_e32 vcc, 0, v0
	s_and_saveexec_b64 s[98:99], vcc
	global_store_dword v9, v10, s[90:91]
	global_store_dword v9, v10, s[92:93]
	s_or_b64 exec, exec, s[98:99]
	s_waitcnt vmcnt(38)
	v_mul_f32_e32 v4, v32, v32
	v_fma_f32 v4, v33, v33, v4
	v_fma_f32 v4, v34, v34, v4
	v_fma_f32 v4, v35, v35, v4
	v_fma_f32 v4, v36, v36, v4
	v_fma_f32 v4, v37, v37, v4
	v_fma_f32 v4, v38, v38, v4
	v_fma_f32 v4, v39, v39, v4
	v_fma_f32 v4, v40, v40, v4
	v_fma_f32 v4, v41, v41, v4
	v_fma_f32 v4, v42, v42, v4
	v_fma_f32 v4, v43, v43, v4
	v_fma_f32 v4, v44, v44, v4
	v_fma_f32 v4, v45, v45, v4
	v_fma_f32 v4, v46, v46, v4
	v_fma_f32 v4, v47, v47, v4
	s_nop 1
	v_add_f32_dpp v5, v4, v4 quad_perm:[1,0,3,2] row_mask:0xf bank_mask:0xf
	s_nop 1
	v_add_f32_dpp v4, v5, v5 quad_perm:[2,3,0,1] row_mask:0xf bank_mask:0xf
	s_nop 1
	v_add_f32_dpp v5, v4, v4 row_half_mirror row_mask:0xf bank_mask:0xf
	s_nop 1
	v_add_f32_dpp v4, v5, v5 row_mirror row_mask:0xf bank_mask:0xf
	s_nop 1
	v_readlane_b32 s98, v4, 0
	v_readlane_b32 s99, v4, 16
	s_nop 3
	v_mov_b32_e32 v5, s98
	v_add_f32_e32 v5, s99, v5
	v_readlane_b32 s98, v4, 32
	v_readlane_b32 s99, v4, 48
	s_nop 3
	v_add_f32_e32 v5, s98, v5
	v_add_f32_e32 v5, s99, v5
	v_mul_f32_e32 v5, 0x3a800000, v5
	v_add_f32_e32 v5, 0x358637bd, v5
	v_rsq_f32_e32 v6, v5
	s_nop 0
	s_add_u32 s98, s97, 13
	v_pk_mul_f32 v[32:33], v[32:33], v[6:7] op_sel_hi:[1,0]
	v_pk_mul_f32 v[34:35], v[34:35], v[6:7] op_sel_hi:[1,0]
	v_pk_mul_f32 v[36:37], v[36:37], v[6:7] op_sel_hi:[1,0]
	v_pk_mul_f32 v[38:39], v[38:39], v[6:7] op_sel_hi:[1,0]
	v_pk_mul_f32 v[40:41], v[40:41], v[6:7] op_sel_hi:[1,0]
	v_pk_mul_f32 v[42:43], v[42:43], v[6:7] op_sel_hi:[1,0]
	v_pk_mul_f32 v[44:45], v[44:45], v[6:7] op_sel_hi:[1,0]
	v_pk_mul_f32 v[46:47], v[46:47], v[6:7] op_sel_hi:[1,0]
	v_pk_mul_f32 v[32:33], v[32:33], v[112:113]
	v_pk_mul_f32 v[34:35], v[34:35], v[114:115]
	v_pk_mul_f32 v[36:37], v[36:37], v[116:117]
	v_pk_mul_f32 v[38:39], v[38:39], v[118:119]
	v_pk_mul_f32 v[40:41], v[40:41], v[120:121]
	v_pk_mul_f32 v[42:43], v[42:43], v[122:123]
	v_pk_mul_f32 v[44:45], v[44:45], v[124:125]
	v_pk_mul_f32 v[46:47], v[46:47], v[126:127]
	v_pk_fma_f32 v[32:33], v[32:33], v[128:129], v[144:145]
	v_pk_fma_f32 v[34:35], v[34:35], v[130:131], v[146:147]
	v_pk_fma_f32 v[36:37], v[36:37], v[132:133], v[148:149]
	v_pk_fma_f32 v[38:39], v[38:39], v[134:135], v[150:151]
	v_pk_fma_f32 v[40:41], v[40:41], v[136:137], v[152:153]
	v_pk_fma_f32 v[42:43], v[42:43], v[138:139], v[154:155]
	v_pk_fma_f32 v[44:45], v[44:45], v[140:141], v[156:157]
	v_pk_fma_f32 v[46:47], v[46:47], v[142:143], v[158:159]
	v_cvt_pk_bf16_f32 v32, v32, v33
	v_cvt_pk_bf16_f32 v33, v34, v35
	v_cvt_pk_bf16_f32 v34, v36, v37
	v_cvt_pk_bf16_f32 v35, v38, v39
	v_cvt_pk_bf16_f32 v36, v40, v41
	v_cvt_pk_bf16_f32 v37, v42, v43
	v_cvt_pk_bf16_f32 v38, v44, v45
	v_cvt_pk_bf16_f32 v39, v46, v47
	s_lshl_b32 s99, s98, 11
	v_lshl_add_u32 v8, v0, 3, s99
	global_store_dwordx2 v8, v[32:33], s[94:95]
	global_store_dwordx2 v8, v[34:35], s[94:95] offset:512
	global_store_dwordx2 v8, v[36:37], s[94:95] offset:1024
	global_store_dwordx2 v8, v[38:39], s[94:95] offset:1536
	s_lshl_b32 s99, s98, 2
	v_mov_b32_e32 v9, s99
	v_mov_b32_e32 v10, 0
	v_cmp_eq_u32_e32 vcc, 0, v0
	s_and_saveexec_b64 s[98:99], vcc
	global_store_dword v9, v10, s[90:91]
	global_store_dword v9, v10, s[92:93]
	s_or_b64 exec, exec, s[98:99]
	s_waitcnt vmcnt(34)
	v_mul_f32_e32 v4, v48, v48
	v_fma_f32 v4, v49, v49, v4
	v_fma_f32 v4, v50, v50, v4
	v_fma_f32 v4, v51, v51, v4
	v_fma_f32 v4, v52, v52, v4
	v_fma_f32 v4, v53, v53, v4
	v_fma_f32 v4, v54, v54, v4
	v_fma_f32 v4, v55, v55, v4
	v_fma_f32 v4, v56, v56, v4
	v_fma_f32 v4, v57, v57, v4
	v_fma_f32 v4, v58, v58, v4
	v_fma_f32 v4, v59, v59, v4
	v_fma_f32 v4, v60, v60, v4
	v_fma_f32 v4, v61, v61, v4
	v_fma_f32 v4, v62, v62, v4
	v_fma_f32 v4, v63, v63, v4
	s_nop 1
	v_add_f32_dpp v5, v4, v4 quad_perm:[1,0,3,2] row_mask:0xf bank_mask:0xf
	s_nop 1
	v_add_f32_dpp v4, v5, v5 quad_perm:[2,3,0,1] row_mask:0xf bank_mask:0xf
	s_nop 1
	v_add_f32_dpp v5, v4, v4 row_half_mirror row_mask:0xf bank_mask:0xf
	s_nop 1
	v_add_f32_dpp v4, v5, v5 row_mirror row_mask:0xf bank_mask:0xf
	s_nop 1
	v_readlane_b32 s98, v4, 0
	v_readlane_b32 s99, v4, 16
	s_nop 3
	v_mov_b32_e32 v5, s98
	v_add_f32_e32 v5, s99, v5
	v_readlane_b32 s98, v4, 32
	v_readlane_b32 s99, v4, 48
	s_nop 3
	v_add_f32_e32 v5, s98, v5
	v_add_f32_e32 v5, s99, v5
	v_mul_f32_e32 v5, 0x3a800000, v5
	v_add_f32_e32 v5, 0x358637bd, v5
	v_rsq_f32_e32 v6, v5
	s_nop 0
	s_add_u32 s98, s97, 14
	v_pk_mul_f32 v[48:49], v[48:49], v[6:7] op_sel_hi:[1,0]
	v_pk_mul_f32 v[50:51], v[50:51], v[6:7] op_sel_hi:[1,0]
	v_pk_mul_f32 v[52:53], v[52:53], v[6:7] op_sel_hi:[1,0]
	v_pk_mul_f32 v[54:55], v[54:55], v[6:7] op_sel_hi:[1,0]
	v_pk_mul_f32 v[56:57], v[56:57], v[6:7] op_sel_hi:[1,0]
	v_pk_mul_f32 v[58:59], v[58:59], v[6:7] op_sel_hi:[1,0]
	v_pk_mul_f32 v[60:61], v[60:61], v[6:7] op_sel_hi:[1,0]
	v_pk_mul_f32 v[62:63], v[62:63], v[6:7] op_sel_hi:[1,0]
	v_pk_mul_f32 v[48:49], v[48:49], v[112:113]
	v_pk_mul_f32 v[50:51], v[50:51], v[114:115]
	v_pk_mul_f32 v[52:53], v[52:53], v[116:117]
	v_pk_mul_f32 v[54:55], v[54:55], v[118:119]
	v_pk_mul_f32 v[56:57], v[56:57], v[120:121]
	v_pk_mul_f32 v[58:59], v[58:59], v[122:123]
	v_pk_mul_f32 v[60:61], v[60:61], v[124:125]
	v_pk_mul_f32 v[62:63], v[62:63], v[126:127]
	v_pk_fma_f32 v[48:49], v[48:49], v[128:129], v[144:145]
	v_pk_fma_f32 v[50:51], v[50:51], v[130:131], v[146:147]
	v_pk_fma_f32 v[52:53], v[52:53], v[132:133], v[148:149]
	v_pk_fma_f32 v[54:55], v[54:55], v[134:135], v[150:151]
	v_pk_fma_f32 v[56:57], v[56:57], v[136:137], v[152:153]
	v_pk_fma_f32 v[58:59], v[58:59], v[138:139], v[154:155]
	v_pk_fma_f32 v[60:61], v[60:61], v[140:141], v[156:157]
	v_pk_fma_f32 v[62:63], v[62:63], v[142:143], v[158:159]
	v_cvt_pk_bf16_f32 v48, v48, v49
	v_cvt_pk_bf16_f32 v49, v50, v51
	v_cvt_pk_bf16_f32 v50, v52, v53
	v_cvt_pk_bf16_f32 v51, v54, v55
	v_cvt_pk_bf16_f32 v52, v56, v57
	v_cvt_pk_bf16_f32 v53, v58, v59
	v_cvt_pk_bf16_f32 v54, v60, v61
	v_cvt_pk_bf16_f32 v55, v62, v63
	s_lshl_b32 s99, s98, 11
	v_lshl_add_u32 v8, v0, 3, s99
	global_store_dwordx2 v8, v[48:49], s[94:95]
	global_store_dwordx2 v8, v[50:51], s[94:95] offset:512
	global_store_dwordx2 v8, v[52:53], s[94:95] offset:1024
	global_store_dwordx2 v8, v[54:55], s[94:95] offset:1536
	s_lshl_b32 s99, s98, 2
	v_mov_b32_e32 v9, s99
	v_mov_b32_e32 v10, 0
	v_cmp_eq_u32_e32 vcc, 0, v0
	s_and_saveexec_b64 s[98:99], vcc
	global_store_dword v9, v10, s[90:91]
	global_store_dword v9, v10, s[92:93]
	s_or_b64 exec, exec, s[98:99]
	s_waitcnt vmcnt(30)
	v_mul_f32_e32 v4, v64, v64
	v_fma_f32 v4, v65, v65, v4
	v_fma_f32 v4, v66, v66, v4
	v_fma_f32 v4, v67, v67, v4
	v_fma_f32 v4, v68, v68, v4
	v_fma_f32 v4, v69, v69, v4
	v_fma_f32 v4, v70, v70, v4
	v_fma_f32 v4, v71, v71, v4
	v_fma_f32 v4, v72, v72, v4
	v_fma_f32 v4, v73, v73, v4
	v_fma_f32 v4, v74, v74, v4
	v_fma_f32 v4, v75, v75, v4
	v_fma_f32 v4, v76, v76, v4
	v_fma_f32 v4, v77, v77, v4
	v_fma_f32 v4, v78, v78, v4
	v_fma_f32 v4, v79, v79, v4
	s_nop 1
	v_add_f32_dpp v5, v4, v4 quad_perm:[1,0,3,2] row_mask:0xf bank_mask:0xf
	s_nop 1
	v_add_f32_dpp v4, v5, v5 quad_perm:[2,3,0,1] row_mask:0xf bank_mask:0xf
	s_nop 1
	v_add_f32_dpp v5, v4, v4 row_half_mirror row_mask:0xf bank_mask:0xf
	s_nop 1
	v_add_f32_dpp v4, v5, v5 row_mirror row_mask:0xf bank_mask:0xf
	s_nop 1
	v_readlane_b32 s98, v4, 0
	v_readlane_b32 s99, v4, 16
	s_nop 3
	v_mov_b32_e32 v5, s98
	v_add_f32_e32 v5, s99, v5
	v_readlane_b32 s98, v4, 32
	v_readlane_b32 s99, v4, 48
	s_nop 3
	v_add_f32_e32 v5, s98, v5
	v_add_f32_e32 v5, s99, v5
	v_mul_f32_e32 v5, 0x3a800000, v5
	v_add_f32_e32 v5, 0x358637bd, v5
	v_rsq_f32_e32 v6, v5
	s_nop 0
	s_add_u32 s98, s97, 15
	v_pk_mul_f32 v[64:65], v[64:65], v[6:7] op_sel_hi:[1,0]
	v_pk_mul_f32 v[66:67], v[66:67], v[6:7] op_sel_hi:[1,0]
	v_pk_mul_f32 v[68:69], v[68:69], v[6:7] op_sel_hi:[1,0]
	v_pk_mul_f32 v[70:71], v[70:71], v[6:7] op_sel_hi:[1,0]
	v_pk_mul_f32 v[72:73], v[72:73], v[6:7] op_sel_hi:[1,0]
	v_pk_mul_f32 v[74:75], v[74:75], v[6:7] op_sel_hi:[1,0]
	v_pk_mul_f32 v[76:77], v[76:77], v[6:7] op_sel_hi:[1,0]
	v_pk_mul_f32 v[78:79], v[78:79], v[6:7] op_sel_hi:[1,0]
	v_pk_mul_f32 v[64:65], v[64:65], v[112:113]
	v_pk_mul_f32 v[66:67], v[66:67], v[114:115]
	v_pk_mul_f32 v[68:69], v[68:69], v[116:117]
	v_pk_mul_f32 v[70:71], v[70:71], v[118:119]
	v_pk_mul_f32 v[72:73], v[72:73], v[120:121]
	v_pk_mul_f32 v[74:75], v[74:75], v[122:123]
	v_pk_mul_f32 v[76:77], v[76:77], v[124:125]
	v_pk_mul_f32 v[78:79], v[78:79], v[126:127]
	v_pk_fma_f32 v[64:65], v[64:65], v[128:129], v[144:145]
	v_pk_fma_f32 v[66:67], v[66:67], v[130:131], v[146:147]
	v_pk_fma_f32 v[68:69], v[68:69], v[132:133], v[148:149]
	v_pk_fma_f32 v[70:71], v[70:71], v[134:135], v[150:151]
	v_pk_fma_f32 v[72:73], v[72:73], v[136:137], v[152:153]
	v_pk_fma_f32 v[74:75], v[74:75], v[138:139], v[154:155]
	v_pk_fma_f32 v[76:77], v[76:77], v[140:141], v[156:157]
	v_pk_fma_f32 v[78:79], v[78:79], v[142:143], v[158:159]
	v_cvt_pk_bf16_f32 v64, v64, v65
	v_cvt_pk_bf16_f32 v65, v66, v67
	v_cvt_pk_bf16_f32 v66, v68, v69
	v_cvt_pk_bf16_f32 v67, v70, v71
	v_cvt_pk_bf16_f32 v68, v72, v73
	v_cvt_pk_bf16_f32 v69, v74, v75
	v_cvt_pk_bf16_f32 v70, v76, v77
	v_cvt_pk_bf16_f32 v71, v78, v79
	s_lshl_b32 s99, s98, 11
	v_lshl_add_u32 v8, v0, 3, s99
	global_store_dwordx2 v8, v[64:65], s[94:95]
	global_store_dwordx2 v8, v[66:67], s[94:95] offset:512
	global_store_dwordx2 v8, v[68:69], s[94:95] offset:1024
	global_store_dwordx2 v8, v[70:71], s[94:95] offset:1536
	s_lshl_b32 s99, s98, 2
	v_mov_b32_e32 v9, s99
	v_mov_b32_e32 v10, 0
	v_cmp_eq_u32_e32 vcc, 0, v0
	s_and_saveexec_b64 s[98:99], vcc
	global_store_dword v9, v10, s[90:91]
	global_store_dword v9, v10, s[92:93]
	s_or_b64 exec, exec, s[98:99]
	s_waitcnt vmcnt(0)
.Lnp1_done:
	v_mbcnt_hi_u32_b32 v32, -1, v210
	s_mov_b64 s[4:5], exec
